# opt8
# baseline (speedup 1.0000x reference)
; template <bool PASS2>
; __device__ __forceinline__ void ssm_block(const P& p, int blk) {
;     ...
;   for (int gi = 0; gi < 4; ++gi) {
;     const int g = wid + 8 * gi;
;     bf16x8 bbf[4];
; #pragma unroll
;     for (int ct = 0; ct < 4; ++ct) bbf[ct] = *(const bf16x8*)(bbfrag + ((size_t)(g * 4 + ct) * 64 + lane) * 8);
;     const float lr = lam[(g * 64 + lane) * 2], li = lam[(g * 64 + lane) * 2 + 1];
;     float xr = 0.f, xi = 0.f;
;     bf16x8 cf[4], df;
;     if (PASS2) {
;       xr = xmeta[(g * 64 + lane) * 2]; xi = xmeta[(g * 64 + lane) * 2 + 1];
;       const float pr = lamP[(g * 64 + lane) * 2], pi = lamP[(g * 64 + lane) * 2 + 1];
;       for (int jj = 0; jj < jb; ++jj) {
;         const float* sp = S + ((size_t)(batch * 8 + jj) * 2048 + g * 64 + lane) * 2;
;         const float nr = pr * xr - pi * xi + sp[0], ni = pr * xi + pi * xr + sp[1];
;         xr = nr; xi = ni;
;       }
.LBB0_348:
	v_lshl_add_u32 v14, s0, 3, v126
	v_lshlrev_b32_e32 v6, 2, v14
	v_ashrrev_i32_e32 v7, 31, v6
	v_or_b32_e32 v2, 1, v6
	v_lshlrev_b64 v[0:1], 10, v[6:7]
	v_ashrrev_i32_e32 v3, 31, v2
	v_lshl_add_u64 v[4:5], v[104:105], 0, v[0:1]
	v_lshlrev_b64 v[2:3], 10, v[2:3]
	v_lshl_add_u64 v[8:9], v[104:105], 0, v[2:3]
	global_load_dwordx4 v[64:67], v[4:5], off
	global_load_dwordx4 v[68:71], v[8:9], off
	v_or_b32_e32 v4, 2, v6
	v_ashrrev_i32_e32 v5, 31, v4
	v_or_b32_e32 v6, 3, v6
	v_lshlrev_b64 v[4:5], 10, v[4:5]
	v_ashrrev_i32_e32 v7, 31, v6
	v_lshl_add_u64 v[8:9], v[104:105], 0, v[4:5]
	v_lshlrev_b64 v[6:7], 10, v[6:7]
	v_lshl_add_u64 v[10:11], v[104:105], 0, v[6:7]
	global_load_dwordx4 v[72:75], v[8:9], off
	global_load_dwordx4 v[76:79], v[10:11], off
	v_lshl_or_b32 v8, v14, 7, v129
	v_ashrrev_i32_e32 v9, 31, v8
	v_lshlrev_b64 v[10:11], 2, v[8:9]
	v_lshl_add_u64 v[12:13], s[78:79], 0, v[10:11]
	v_lshl_add_u64 v[10:11], s[22:23], 0, v[10:11]
	global_load_dwordx2 v[118:119], v[12:13], off
	global_load_dwordx2 v[124:125], v[10:11], off
	s_andn2_b64 vcc, exec, s[24:25]
	s_cbranch_vccnz .LBB0_351
	v_lshl_add_u64 v[8:9], v[8:9], 2, s[20:21]
	global_load_dwordx2 v[8:9], v[8:9], off
	v_mov_b64_e32 v[10:11], v[110:111]
	global_load_dwordx2 v[144:145], v[10:11], off
	s_cmp_lt_u32 s81, 2
	s_cbranch_scc1 .Lssm2_ld_done
	v_lshl_add_u64 v[10:11], v[10:11], 0, s[26:27]
	global_load_dwordx2 v[146:147], v[10:11], off
	s_cmp_lt_u32 s81, 3
	s_cbranch_scc1 .Lssm2_ld_done
	v_lshl_add_u64 v[10:11], v[10:11], 0, s[26:27]
	global_load_dwordx2 v[148:149], v[10:11], off
	s_cmp_lt_u32 s81, 4
	s_cbranch_scc1 .Lssm2_ld_done
	v_lshl_add_u64 v[10:11], v[10:11], 0, s[26:27]
	global_load_dwordx2 v[150:151], v[10:11], off
	s_cmp_lt_u32 s81, 5
	s_cbranch_scc1 .Lssm2_ld_done
	v_lshl_add_u64 v[10:11], v[10:11], 0, s[26:27]
	global_load_dwordx2 v[152:153], v[10:11], off
	s_cmp_lt_u32 s81, 6
	s_cbranch_scc1 .Lssm2_ld_done
	v_lshl_add_u64 v[10:11], v[10:11], 0, s[26:27]
	global_load_dwordx2 v[154:155], v[10:11], off
	s_cmp_lt_u32 s81, 7
	s_cbranch_scc1 .Lssm2_ld_done
	v_lshl_add_u64 v[10:11], v[10:11], 0, s[26:27]
	global_load_dwordx2 v[156:157], v[10:11], off
.Lssm2_ld_done:
	s_waitcnt vmcnt(0)
	v_mov_b32_e32 v12, v8
	v_mov_b32_e32 v13, v8
	v_mov_b32_e32 v8, v9
	v_pk_mul_f32 v[18:19], v[8:9], v[124:125] op_sel:[0,1] op_sel_hi:[1,0]
	v_pk_fma_f32 v[20:21], v[12:13], v[124:125], v[18:19] neg_lo:[0,0,1] neg_hi:[0,0,1]
	v_pk_fma_f32 v[18:19], v[12:13], v[124:125], v[18:19]
	v_mov_b32_e32 v21, v19
	v_pk_add_f32 v[124:125], v[20:21], v[144:145]
	s_cmp_eq_u32 s81, 1
	s_cbranch_scc1 .LBB0_351
	v_pk_mul_f32 v[18:19], v[8:9], v[124:125] op_sel:[0,1] op_sel_hi:[1,0]
	v_pk_fma_f32 v[20:21], v[12:13], v[124:125], v[18:19] neg_lo:[0,0,1] neg_hi:[0,0,1]
	v_pk_fma_f32 v[18:19], v[12:13], v[124:125], v[18:19]
	v_mov_b32_e32 v21, v19
	v_pk_add_f32 v[124:125], v[20:21], v[146:147]
	s_cmp_eq_u32 s81, 2
	s_cbranch_scc1 .LBB0_351
	v_pk_mul_f32 v[18:19], v[8:9], v[124:125] op_sel:[0,1] op_sel_hi:[1,0]
	v_pk_fma_f32 v[20:21], v[12:13], v[124:125], v[18:19] neg_lo:[0,0,1] neg_hi:[0,0,1]
	v_pk_fma_f32 v[18:19], v[12:13], v[124:125], v[18:19]
	v_mov_b32_e32 v21, v19
	v_pk_add_f32 v[124:125], v[20:21], v[148:149]
	s_cmp_eq_u32 s81, 3
	s_cbranch_scc1 .LBB0_351
	v_pk_mul_f32 v[18:19], v[8:9], v[124:125] op_sel:[0,1] op_sel_hi:[1,0]
	v_pk_fma_f32 v[20:21], v[12:13], v[124:125], v[18:19] neg_lo:[0,0,1] neg_hi:[0,0,1]
	v_pk_fma_f32 v[18:19], v[12:13], v[124:125], v[18:19]
	v_mov_b32_e32 v21, v19
	v_pk_add_f32 v[124:125], v[20:21], v[150:151]
	s_cmp_eq_u32 s81, 4
	s_cbranch_scc1 .LBB0_351
	v_pk_mul_f32 v[18:19], v[8:9], v[124:125] op_sel:[0,1] op_sel_hi:[1,0]
	v_pk_fma_f32 v[20:21], v[12:13], v[124:125], v[18:19] neg_lo:[0,0,1] neg_hi:[0,0,1]
	v_pk_fma_f32 v[18:19], v[12:13], v[124:125], v[18:19]
	v_mov_b32_e32 v21, v19
	v_pk_add_f32 v[124:125], v[20:21], v[152:153]
	s_cmp_eq_u32 s81, 5
	s_cbranch_scc1 .LBB0_351
	v_pk_mul_f32 v[18:19], v[8:9], v[124:125] op_sel:[0,1] op_sel_hi:[1,0]
	v_pk_fma_f32 v[20:21], v[12:13], v[124:125], v[18:19] neg_lo:[0,0,1] neg_hi:[0,0,1]
	v_pk_fma_f32 v[18:19], v[12:13], v[124:125], v[18:19]
	v_mov_b32_e32 v21, v19
	v_pk_add_f32 v[124:125], v[20:21], v[154:155]
	s_cmp_eq_u32 s81, 6
	s_cbranch_scc1 .LBB0_351
	v_pk_mul_f32 v[18:19], v[8:9], v[124:125] op_sel:[0,1] op_sel_hi:[1,0]
	v_pk_fma_f32 v[20:21], v[12:13], v[124:125], v[18:19] neg_lo:[0,0,1] neg_hi:[0,0,1]
	v_pk_fma_f32 v[18:19], v[12:13], v[124:125], v[18:19]
	v_mov_b32_e32 v21, v19
	v_pk_add_f32 v[124:125], v[20:21], v[156:157]

; __device__ __forceinline__ float sigm(float x) { return __builtin_amdgcn_rcpf(1.f + __expf(-x)); }
; template <bool PASS2>
; __device__ __forceinline__ void ssm_block(const P& p, int blk) {
;     ...
;           {
;             bf16x8 au = {0, 0, 0, 0, 0, 0, 0, 0};
;             if (q4 < 2) au = *(const bf16x8*)(proj + (size_t)(sc * 32 + rt * 16 + l15) * 4096 + 1536 + g * 16 + q4 * 8);
;             acc = __builtin_amdgcn_mfma_f32_16x16x32_bf16(au, df, acc, 0, 0, 0);
;           }
; #pragma unroll
;           for (int r = 0; r < 4; ++r) {
;             const int t = rt * 16 + q4 * 4 + r;
;             const float y = acc[r];
;             const float ge = y * sigm(1.5957691216057308f * (y + 0.044715f * y * y * y));
;             proj[(size_t)(sc * 32 + t) * 4096 + 1536 + g * 16 + l15] = f2bf(ge);
;           }
;         }
.LBB0_352:
	s_waitcnt vmcnt(4)
	v_mfma_f32_16x16x32_bf16 v[0:3], v[136:139], v[96:99], v[4:7]
	s_add_u32 s34, s34, 0x40000
	s_addc_u32 s35, s35, 0
	s_cmp_eq_u32 s34, 0x200000
	s_nop 4
	v_mul_f32_e32 v4, 0x3d372713, v0
	v_mul_f32_e32 v4, v0, v4
	v_fma_f32 v4, v0, v4, v0
	v_mul_f32_e32 v5, 0x3d372713, v1
	v_mul_f32_e32 v4, 0x3fcc422a, v4
	v_mul_f32_e32 v5, v1, v5
	v_mul_f32_e32 v4, 0xbfb8aa3b, v4
	v_fma_f32 v5, v1, v5, v1
	v_exp_f32_e32 v4, v4
	v_mul_f32_e32 v5, 0x3fcc422a, v5
	v_mul_f32_e32 v5, 0xbfb8aa3b, v5
	v_exp_f32_e32 v6, v5
	v_mul_f32_e32 v7, 0x3d372713, v2
	v_add_f32_e32 v4, 1.0, v4
	v_mul_f32_e32 v7, v2, v7
	v_rcp_f32_e32 v4, v4
	v_fma_f32 v7, v2, v7, v2
	v_add_f32_e32 v6, 1.0, v6
	v_mul_f32_e32 v7, 0x3fcc422a, v7
	v_rcp_f32_e32 v6, v6
	v_mul_f32_e32 v7, 0xbfb8aa3b, v7
	v_exp_f32_e32 v7, v7
	v_mul_f32_e32 v0, v0, v4
	v_add_co_u32_e32 v4, vcc, s42, v8
	v_cvt_pk_bf16_f32 v0, v0, s0
	s_nop 0
	v_addc_co_u32_e32 v5, vcc, 0, v9, vcc
	global_store_short v[4:5], v0, off offset:3072
	v_mul_f32_e32 v0, v1, v6
	v_cvt_pk_bf16_f32 v4, v0, s0
	v_add_f32_e32 v0, 1.0, v7
	v_rcp_f32_e32 v5, v0
	v_add_co_u32_e32 v0, vcc, s43, v8
	s_nop 1
	v_addc_co_u32_e32 v1, vcc, 0, v9, vcc
	global_store_short v[0:1], v4, off offset:3072
	v_mul_f32_e32 v1, 0x3d372713, v3
	v_mul_f32_e32 v1, v3, v1
	v_fma_f32 v1, v3, v1, v3
	v_mul_f32_e32 v1, 0x3fcc422a, v1
	v_mul_f32_e32 v1, 0xbfb8aa3b, v1
	v_exp_f32_e32 v1, v1
	v_mul_f32_e32 v0, v2, v5
	v_cvt_pk_bf16_f32 v2, v0, s0
	v_add_co_u32_e32 v0, vcc, s44, v8
	v_add_f32_e32 v1, 1.0, v1
	v_rcp_f32_e32 v4, v1
	v_addc_co_u32_e32 v1, vcc, 0, v9, vcc
	global_store_short v[0:1], v2, off offset:3072
	v_mul_f32_e32 v0, v3, v4
	v_cvt_pk_bf16_f32 v2, v0, s0
	v_add_co_u32_e32 v0, vcc, 0xad26000, v8
	s_nop 1
	v_addc_co_u32_e32 v1, vcc, 0, v9, vcc
	global_store_short v[0:1], v2, off offset:3072
	v_mov_b64_e32 v[0:1], v[100:101]
	v_mov_b64_e32 v[2:3], v[102:103]
	s_cbranch_scc1 .LBB0_347

; template <bool PASS2>
; __device__ __forceinline__ void ssm_block(const P& p, int blk) {
;     ...
;     for (int sc = 0; sc < 8; ++sc) {
;       const bf16x8 ua = ufr;
;       if (sc < 7) ufr = *(const bf16x8*)(proj + (size_t)((sc + 1) * 32 + l31) * 4096 + 1536 + g * 16 + hi * 8);
;       f32x16 d0, d1, d2, d3;
;       {
;         const f32x16 z = {0.f, 0.f, 0.f, 0.f, 0.f, 0.f, 0.f, 0.f, 0.f, 0.f, 0.f, 0.f, 0.f, 0.f, 0.f, 0.f};
;         d0 = __builtin_amdgcn_mfma_f32_32x32x16_bf16(ua, bbf[0], z, 0, 0, 0);
;         d1 = __builtin_amdgcn_mfma_f32_32x32x16_bf16(ua, bbf[1], z, 0, 0, 0);
;         d2 = __builtin_amdgcn_mfma_f32_32x32x16_bf16(ua, bbf[2], z, 0, 0, 0);
;         d3 = __builtin_amdgcn_mfma_f32_32x32x16_bf16(ua, bbf[3], z, 0, 0, 0);
;       }
; #pragma unroll
;       for (int r = 0; r < 16; ++r) {
;         auto s01 = __builtin_amdgcn_permlane32_swap(__float_as_uint(d0[r]), __float_as_uint(d1[r]), false, false);
;         d0[r] = __uint_as_float(s01[0]); d1[r] = __uint_as_float(s01[1]);
;         auto s23 = __builtin_amdgcn_permlane32_swap(__float_as_uint(d2[r]), __float_as_uint(d3[r]), false, false);
;         d2[r] = __uint_as_float(s23[0]); d3[r] = __uint_as_float(s23[1]);
;       }
; #pragma unroll
;       for (int t = 0; t < 32; ++t) {
;         const int r = (t & 3) + 4 * (t >> 3);
;         const float bur = ((t >> 2) & 1) ? d1[r] : d0[r];
;         const float bui = ((t >> 2) & 1) ? d3[r] : d2[r];
;         const float nr = lr * xr - li * xi + bur, ni = lr * xi + li * xr + bui;
;         xr = nr; xi = ni;
;         if (PASS2) { xs[t * XS_STRIDE + lane] = f2bf(xr); xs[t * XS_STRIDE + 64 + lane] = f2bf(xi); }
;     ...
;           {
;             bf16x8 au = {0, 0, 0, 0, 0, 0, 0, 0};
;             if (q4 < 2) au = *(const bf16x8*)(proj + (size_t)(sc * 32 + rt * 16 + l15) * 4096 + 1536 + g * 16 + q4 * 8);
.LBB0_355:
	v_mov_b32_e32 v132, 0
	v_mov_b32_e32 v133, 0
	v_mov_b32_e32 v134, 0
	v_mov_b32_e32 v135, 0
	v_mov_b32_e32 v136, 0
	v_mov_b32_e32 v137, 0
	v_mov_b32_e32 v138, 0
	v_mov_b32_e32 v139, 0
	v_lshl_add_u64 v[140:141], v[114:115], 0, s[34:35]
	s_and_saveexec_b64 s[36:37], s[4:5]
	v_add_co_u32_e32 v142, vcc, 0xad00000, v140
	s_nop 1
	v_addc_co_u32_e32 v143, vcc, 0, v141, vcc
	global_load_dwordx4 v[132:135], v[142:143], off offset:3072
	v_add_co_u32_e32 v142, vcc, 0xad20000, v140
	s_nop 1
	v_addc_co_u32_e32 v143, vcc, 0, v141, vcc
	global_load_dwordx4 v[136:139], v[142:143], off offset:3072
	s_or_b64 exec, exec, s[36:37]
	v_mfma_f32_32x32x16_bf16 v[48:63], v[0:3], v[64:67], 0
	v_mul_f32_e32 v131, v119, v125
	v_fma_f32 v131, v118, v124, -v131
	v_mul_f32_e32 v125, v118, v125
	v_fmac_f32_e32 v125, v119, v124
	v_mfma_f32_32x32x16_bf16 v[16:31], v[0:3], v[68:71], 0
	v_mfma_f32_32x32x16_bf16 v[32:47], v[0:3], v[72:75], 0
	s_nop 10
	v_permlane32_swap_b32_e32 v48, v16
	v_add_f32_e32 v48, v131, v48
	v_cvt_pk_bf16_f32 v124, v48, s0
	ds_write_b16 v128, v124
	v_permlane32_swap_b32_e32 v49, v17
	v_mfma_f32_32x32x16_bf16 v[0:15], v[0:3], v[76:79], 0
	v_permlane32_swap_b32_e32 v50, v18
	v_permlane32_swap_b32_e32 v51, v19
	v_permlane32_swap_b32_e32 v52, v20
	v_permlane32_swap_b32_e32 v53, v21
	s_nop 7
	v_permlane32_swap_b32_e32 v32, v0
	v_add_f32_e32 v32, v125, v32
	v_cvt_pk_bf16_f32 v124, v32, s0
	ds_write_b16 v128, v124 offset:128
	v_mul_f32_e32 v124, v119, v32
	v_fma_f32 v124, v118, v48, -v124
	v_mul_f32_e32 v32, v118, v32
	v_permlane32_swap_b32_e32 v33, v1
	v_add_f32_e32 v49, v124, v49
	v_fmac_f32_e32 v32, v119, v48
	v_add_f32_e32 v32, v32, v33
	v_cvt_pk_bf16_f32 v33, v49, s0
	ds_write_b16 v128, v33 offset:272
	v_cvt_pk_bf16_f32 v33, v32, s0
	ds_write_b16 v128, v33 offset:400
	v_mul_f32_e32 v33, v119, v32
	v_fma_f32 v33, v118, v49, -v33
	v_mul_f32_e32 v48, v119, v49
	v_permlane32_swap_b32_e32 v34, v2
	v_add_f32_e32 v33, v33, v50
	v_fmac_f32_e32 v48, v118, v32
	v_add_f32_e32 v32, v48, v34
	v_cvt_pk_bf16_f32 v34, v33, s0
	ds_write_b16 v128, v34 offset:544
	v_cvt_pk_bf16_f32 v34, v32, s0
	ds_write_b16 v128, v34 offset:672
	v_mul_f32_e32 v34, v119, v32
	v_fma_f32 v34, v118, v33, -v34
	v_mul_f32_e32 v33, v119, v33
	v_permlane32_swap_b32_e32 v35, v3
	v_add_f32_e32 v34, v34, v51
	v_fmac_f32_e32 v33, v118, v32
	v_add_f32_e32 v32, v33, v35
	v_cvt_pk_bf16_f32 v33, v34, s0
	ds_write_b16 v128, v33 offset:816
	v_cvt_pk_bf16_f32 v33, v32, s0
	ds_write_b16 v128, v33 offset:944
	v_mul_f32_e32 v33, v119, v32
	v_fma_f32 v33, v118, v34, -v33
	v_add_f32_e32 v16, v33, v16
	v_mul_f32_e32 v33, v119, v34
	v_fmac_f32_e32 v33, v118, v32
	v_add_f32_e32 v0, v33, v0
	v_cvt_pk_bf16_f32 v32, v16, s0
	ds_write_b16 v128, v32 offset:1088
	v_cvt_pk_bf16_f32 v32, v0, s0
	ds_write_b16 v128, v32 offset:1216
	v_mul_f32_e32 v32, v119, v0
	v_fma_f32 v32, v118, v16, -v32
	v_mul_f32_e32 v16, v119, v16
	v_add_f32_e32 v17, v32, v17
	v_fmac_f32_e32 v16, v118, v0
	v_add_f32_e32 v0, v16, v1
	v_cvt_pk_bf16_f32 v1, v17, s0
	ds_write_b16 v128, v1 offset:1360
	v_cvt_pk_bf16_f32 v1, v0, s0
	ds_write_b16 v128, v1 offset:1488
	v_mul_f32_e32 v1, v119, v0
	v_fma_f32 v1, v118, v17, -v1
	v_mul_f32_e32 v16, v119, v17
	v_add_f32_e32 v1, v1, v18
	v_fmac_f32_e32 v16, v118, v0
	v_add_f32_e32 v0, v16, v2
	v_cvt_pk_bf16_f32 v2, v1, s0
	ds_write_b16 v128, v2 offset:1632
	v_cvt_pk_bf16_f32 v2, v0, s0
	ds_write_b16 v128, v2 offset:1760
	v_mul_f32_e32 v2, v119, v0
	v_fma_f32 v2, v118, v1, -v2
	v_mul_f32_e32 v1, v119, v1
	v_add_f32_e32 v2, v2, v19
	v_fmac_f32_e32 v1, v118, v0
	v_add_f32_e32 v0, v1, v3
	v_cvt_pk_bf16_f32 v1, v2, s0
	ds_write_b16 v128, v1 offset:1904
	v_cvt_pk_bf16_f32 v1, v0, s0
	ds_write_b16 v128, v1 offset:2032
	v_mul_f32_e32 v1, v119, v0
	v_fma_f32 v1, v118, v2, -v1
	v_mul_f32_e32 v2, v119, v2
	v_permlane32_swap_b32_e32 v36, v4
	v_add_f32_e32 v1, v1, v52
	v_fmac_f32_e32 v2, v118, v0
	v_add_f32_e32 v0, v2, v36
	v_cvt_pk_bf16_f32 v2, v1, s0
	ds_write_b16 v128, v2 offset:2176
	v_cvt_pk_bf16_f32 v2, v0, s0
	ds_write_b16 v128, v2 offset:2304
	v_mul_f32_e32 v2, v119, v0
	v_fma_f32 v2, v118, v1, -v2
	v_mul_f32_e32 v1, v119, v1
	v_permlane32_swap_b32_e32 v37, v5
	v_add_f32_e32 v2, v2, v53
	v_fmac_f32_e32 v1, v118, v0
	v_add_f32_e32 v0, v1, v37
	v_cvt_pk_bf16_f32 v1, v2, s0
	ds_write_b16 v128, v1 offset:2448
	v_cvt_pk_bf16_f32 v1, v0, s0
	ds_write_b16 v128, v1 offset:2576
	v_mul_f32_e32 v1, v119, v0
	v_permlane32_swap_b32_e32 v54, v22
	v_fma_f32 v1, v118, v2, -v1
	v_mul_f32_e32 v2, v119, v2
	v_permlane32_swap_b32_e32 v38, v6
	v_add_f32_e32 v1, v1, v54
	v_fmac_f32_e32 v2, v118, v0
	v_add_f32_e32 v0, v2, v38
	v_cvt_pk_bf16_f32 v2, v1, s0
	ds_write_b16 v128, v2 offset:2720
	v_cvt_pk_bf16_f32 v2, v0, s0
	ds_write_b16 v128, v2 offset:2848
	v_mul_f32_e32 v2, v119, v0
	v_permlane32_swap_b32_e32 v55, v23
	v_fma_f32 v2, v118, v1, -v2
	v_mul_f32_e32 v1, v119, v1
	v_permlane32_swap_b32_e32 v39, v7
	v_add_f32_e32 v2, v2, v55
	v_fmac_f32_e32 v1, v118, v0
	v_add_f32_e32 v0, v1, v39
	v_cvt_pk_bf16_f32 v1, v2, s0
	ds_write_b16 v128, v1 offset:2992
	v_cvt_pk_bf16_f32 v1, v0, s0
	ds_write_b16 v128, v1 offset:3120
	v_mul_f32_e32 v1, v119, v0
	v_fma_f32 v1, v118, v2, -v1
	v_mul_f32_e32 v2, v119, v2
	v_add_f32_e32 v1, v1, v20
	v_fmac_f32_e32 v2, v118, v0
	v_add_f32_e32 v0, v2, v4
	v_cvt_pk_bf16_f32 v2, v1, s0
	ds_write_b16 v128, v2 offset:3264
	v_cvt_pk_bf16_f32 v2, v0, s0
	ds_write_b16 v128, v2 offset:3392
	v_mul_f32_e32 v2, v119, v0
	v_fma_f32 v2, v118, v1, -v2
	v_mul_f32_e32 v1, v119, v1
	v_add_f32_e32 v2, v2, v21
	v_fmac_f32_e32 v1, v118, v0
	v_add_f32_e32 v0, v1, v5
	v_cvt_pk_bf16_f32 v1, v2, s0
	ds_write_b16 v128, v1 offset:3536
; template <bool PASS2>
; __device__ __forceinline__ void ssm_block(const P& p, int blk) {
;     ...
; #pragma unroll
;       for (int t = 0; t < 32; ++t) {
;         const int r = (t & 3) + 4 * (t >> 3);
;         const float bur = ((t >> 2) & 1) ? d1[r] : d0[r];
;         const float bui = ((t >> 2) & 1) ? d3[r] : d2[r];
;         const float nr = lr * xr - li * xi + bur, ni = lr * xi + li * xr + bui;
;         xr = nr; xi = ni;
;         if (PASS2) { xs[t * XS_STRIDE + lane] = f2bf(xr); xs[t * XS_STRIDE + 64 + lane] = f2bf(xi); }
;       }
;       if (PASS2) {
;         __builtin_amdgcn_wave_barrier();
;         const int l15 = lane & 15, q4 = lane >> 4;
; #pragma unroll
;         for (int rt = 0; rt < 2; ++rt) {
;           f32x4 acc = f32x4{0.f, 0.f, 0.f, 0.f};
; #pragma unroll
;           for (int kk = 0; kk < 4; ++kk) {
;             bf16x8 af = *(const bf16x8*)(xs + (rt * 16 + l15) * XS_STRIDE + kk * 32 + q4 * 8);
	v_cvt_pk_bf16_f32 v1, v0, s0
	ds_write_b16 v128, v1 offset:3664
	v_mul_f32_e32 v1, v119, v0
	v_fma_f32 v1, v118, v2, -v1
	v_mul_f32_e32 v2, v119, v2
	v_add_f32_e32 v1, v1, v22
	v_fmac_f32_e32 v2, v118, v0
	v_add_f32_e32 v0, v2, v6
	v_cvt_pk_bf16_f32 v2, v1, s0
	ds_write_b16 v128, v2 offset:3808
	v_cvt_pk_bf16_f32 v2, v0, s0
	ds_write_b16 v128, v2 offset:3936
	v_mul_f32_e32 v2, v119, v0
	v_fma_f32 v2, v118, v1, -v2
	v_mul_f32_e32 v1, v119, v1
	v_add_f32_e32 v2, v2, v23
	v_fmac_f32_e32 v1, v118, v0
	v_add_f32_e32 v0, v1, v7
	v_cvt_pk_bf16_f32 v1, v2, s0
	ds_write_b16 v128, v1 offset:4080
	v_cvt_pk_bf16_f32 v1, v0, s0
	ds_write_b16 v128, v1 offset:4208
	v_mul_f32_e32 v1, v119, v0
	v_permlane32_swap_b32_e32 v56, v24
	v_fma_f32 v1, v118, v2, -v1
	v_mul_f32_e32 v2, v119, v2
	v_permlane32_swap_b32_e32 v40, v8
	v_add_f32_e32 v1, v1, v56
	v_fmac_f32_e32 v2, v118, v0
	v_add_f32_e32 v0, v2, v40
	v_cvt_pk_bf16_f32 v2, v1, s0
	ds_write_b16 v128, v2 offset:4352
	v_cvt_pk_bf16_f32 v2, v0, s0
	ds_write_b16 v128, v2 offset:4480
	v_mul_f32_e32 v2, v119, v0
	v_permlane32_swap_b32_e32 v57, v25
	v_fma_f32 v2, v118, v1, -v2
	v_mul_f32_e32 v1, v119, v1
	v_permlane32_swap_b32_e32 v41, v9
	v_add_f32_e32 v2, v2, v57
	v_fmac_f32_e32 v1, v118, v0
	v_add_f32_e32 v0, v1, v41
	v_cvt_pk_bf16_f32 v1, v2, s0
	ds_write_b16 v128, v1 offset:4624
	v_cvt_pk_bf16_f32 v1, v0, s0
	ds_write_b16 v128, v1 offset:4752
	v_mul_f32_e32 v1, v119, v0
	v_permlane32_swap_b32_e32 v58, v26
	v_fma_f32 v1, v118, v2, -v1
	v_mul_f32_e32 v2, v119, v2
	v_permlane32_swap_b32_e32 v42, v10
	v_add_f32_e32 v1, v1, v58
	v_fmac_f32_e32 v2, v118, v0
	v_add_f32_e32 v0, v2, v42
	v_cvt_pk_bf16_f32 v2, v1, s0
	ds_write_b16 v128, v2 offset:4896
	v_cvt_pk_bf16_f32 v2, v0, s0
	ds_write_b16 v128, v2 offset:5024
	v_mul_f32_e32 v2, v119, v0
	v_permlane32_swap_b32_e32 v59, v27
	v_fma_f32 v2, v118, v1, -v2
	v_mul_f32_e32 v1, v119, v1
	v_permlane32_swap_b32_e32 v43, v11
	v_add_f32_e32 v2, v2, v59
	v_fmac_f32_e32 v1, v118, v0
	v_add_f32_e32 v0, v1, v43
	v_cvt_pk_bf16_f32 v1, v2, s0
	ds_write_b16 v128, v1 offset:5168
	v_cvt_pk_bf16_f32 v1, v0, s0
	ds_write_b16 v128, v1 offset:5296
	v_mul_f32_e32 v1, v119, v0
	v_fma_f32 v1, v118, v2, -v1
	v_mul_f32_e32 v2, v119, v2
	v_add_f32_e32 v1, v1, v24
	v_fmac_f32_e32 v2, v118, v0
	v_add_f32_e32 v0, v2, v8
	v_cvt_pk_bf16_f32 v2, v1, s0
	ds_write_b16 v128, v2 offset:5440
	v_cvt_pk_bf16_f32 v2, v0, s0
	ds_write_b16 v128, v2 offset:5568
	v_mul_f32_e32 v2, v119, v0
	v_fma_f32 v2, v118, v1, -v2
	v_mul_f32_e32 v1, v119, v1
	v_add_f32_e32 v2, v2, v25
	v_fmac_f32_e32 v1, v118, v0
	v_add_f32_e32 v0, v1, v9
	v_cvt_pk_bf16_f32 v1, v2, s0
	ds_write_b16 v128, v1 offset:5712
	v_cvt_pk_bf16_f32 v1, v0, s0
	ds_write_b16 v128, v1 offset:5840
	v_mul_f32_e32 v1, v119, v0
	v_fma_f32 v1, v118, v2, -v1
	v_mul_f32_e32 v2, v119, v2
	v_add_f32_e32 v1, v1, v26
	v_fmac_f32_e32 v2, v118, v0
	v_add_f32_e32 v0, v2, v10
	v_cvt_pk_bf16_f32 v2, v1, s0
	ds_write_b16 v128, v2 offset:5984
	v_cvt_pk_bf16_f32 v2, v0, s0
	ds_write_b16 v128, v2 offset:6112
	v_mul_f32_e32 v2, v119, v0
	v_fma_f32 v2, v118, v1, -v2
	v_mul_f32_e32 v1, v119, v1
	v_add_f32_e32 v2, v2, v27
	v_fmac_f32_e32 v1, v118, v0
	v_add_f32_e32 v0, v1, v11
	v_cvt_pk_bf16_f32 v1, v2, s0
	ds_write_b16 v128, v1 offset:6256
	v_cvt_pk_bf16_f32 v1, v0, s0
	ds_write_b16 v128, v1 offset:6384
	v_mul_f32_e32 v1, v119, v0
	v_permlane32_swap_b32_e32 v60, v28
	v_fma_f32 v1, v118, v2, -v1
	v_mul_f32_e32 v2, v119, v2
	v_permlane32_swap_b32_e32 v44, v12
	v_add_f32_e32 v1, v1, v60
	v_fmac_f32_e32 v2, v118, v0
	v_add_f32_e32 v0, v2, v44
	v_cvt_pk_bf16_f32 v2, v1, s0
	ds_write_b16 v128, v2 offset:6528
	v_cvt_pk_bf16_f32 v2, v0, s0
	ds_write_b16 v128, v2 offset:6656
	v_mul_f32_e32 v2, v119, v0
	v_permlane32_swap_b32_e32 v61, v29
	v_fma_f32 v2, v118, v1, -v2
	v_mul_f32_e32 v1, v119, v1
	v_permlane32_swap_b32_e32 v45, v13
	v_add_f32_e32 v2, v2, v61
	v_fmac_f32_e32 v1, v118, v0
	v_add_f32_e32 v0, v1, v45
	v_cvt_pk_bf16_f32 v1, v2, s0
	ds_write_b16 v128, v1 offset:6800
	v_cvt_pk_bf16_f32 v1, v0, s0
	ds_write_b16 v128, v1 offset:6928
	v_mul_f32_e32 v1, v119, v0
	v_permlane32_swap_b32_e32 v62, v30
	v_fma_f32 v1, v118, v2, -v1
	v_mul_f32_e32 v2, v119, v2
	v_permlane32_swap_b32_e32 v46, v14
	v_add_f32_e32 v1, v1, v62
	v_fmac_f32_e32 v2, v118, v0
	v_add_f32_e32 v0, v2, v46
	v_cvt_pk_bf16_f32 v2, v1, s0
	ds_write_b16 v128, v2 offset:7072
	v_cvt_pk_bf16_f32 v2, v0, s0
	ds_write_b16 v128, v2 offset:7200
	v_mul_f32_e32 v2, v119, v0
	v_permlane32_swap_b32_e32 v63, v31
	v_fma_f32 v2, v118, v1, -v2
	v_mul_f32_e32 v1, v119, v1
	v_permlane32_swap_b32_e32 v47, v15
	v_add_f32_e32 v2, v2, v63
	v_fmac_f32_e32 v1, v118, v0
	v_add_f32_e32 v3, v1, v47
	v_cvt_pk_bf16_f32 v0, v2, s0
	ds_write_b16 v128, v0 offset:7344
	v_cvt_pk_bf16_f32 v0, v3, s0
	ds_write_b16 v128, v0 offset:7472
	v_mul_f32_e32 v0, v119, v3
	v_mul_f32_e32 v1, v119, v2
	v_fma_f32 v0, v118, v2, -v0
	v_fmac_f32_e32 v1, v118, v3
	v_mov_b32_e32 v2, v28
	v_mov_b32_e32 v3, v12
	v_pk_add_f32 v[0:1], v[0:1], v[2:3]
	v_mov_b32_e32 v12, v29
	v_cvt_pk_bf16_f32 v2, v0, s0
	ds_write_b16 v128, v2 offset:7616
	v_cvt_pk_bf16_f32 v2, v1, s0
	ds_write_b16 v128, v2 offset:7744
	v_pk_mul_f32 v[2:3], v[122:123], v[0:1]
	v_mov_b32_e32 v4, v30
	v_pk_fma_f32 v[6:7], v[120:121], v[0:1], v[2:3] op_sel:[0,0,1] op_sel_hi:[1,1,0] neg_lo:[0,0,1] neg_hi:[0,0,1]
	v_pk_fma_f32 v[0:1], v[120:121], v[0:1], v[2:3] op_sel:[0,0,1] op_sel_hi:[1,1,0]
	v_mov_b32_e32 v5, v14
	v_mov_b32_e32 v7, v1
	v_pk_add_f32 v[0:1], v[6:7], v[12:13]
	v_mov_b32_e32 v14, v31
	v_cvt_pk_bf16_f32 v2, v0, s0
	ds_write_b16 v128, v2 offset:7888
	v_cvt_pk_bf16_f32 v2, v1, s0
	ds_write_b16 v128, v2 offset:8016
	v_pk_mul_f32 v[2:3], v[122:123], v[0:1]
	s_nop 0
	v_pk_fma_f32 v[6:7], v[120:121], v[0:1], v[2:3] op_sel:[0,0,1] op_sel_hi:[1,1,0] neg_lo:[0,0,1] neg_hi:[0,0,1]
	v_pk_fma_f32 v[0:1], v[120:121], v[0:1], v[2:3] op_sel:[0,0,1] op_sel_hi:[1,1,0]
	s_nop 0
	v_mov_b32_e32 v7, v1
	v_pk_add_f32 v[0:1], v[6:7], v[4:5]
	s_nop 0
	v_cvt_pk_bf16_f32 v2, v0, s0
	ds_write_b16 v128, v2 offset:8160
	v_cvt_pk_bf16_f32 v2, v1, s0
	ds_write_b16 v128, v2 offset:8288
	v_pk_mul_f32 v[2:3], v[122:123], v[0:1]
	s_nop 0
	v_pk_fma_f32 v[4:5], v[120:121], v[0:1], v[2:3] op_sel:[0,0,1] op_sel_hi:[1,1,0] neg_lo:[0,0,1] neg_hi:[0,0,1]
	v_pk_fma_f32 v[0:1], v[120:121], v[0:1], v[2:3] op_sel:[0,0,1] op_sel_hi:[1,1,0]
	s_nop 0
	v_mov_b32_e32 v5, v1
	v_pk_add_f32 v[124:125], v[4:5], v[14:15]
	s_nop 0
	v_cvt_pk_bf16_f32 v0, v124, s0
	ds_write_b16 v128, v0 offset:8432
	v_cvt_pk_bf16_f32 v0, v125, s0
	ds_write_b16 v128, v0 offset:8560
	ds_read_b128 v[0:3], v130
	ds_read_b128 v[4:7], v130 offset:64
	s_waitcnt lgkmcnt(1)
; __device__ __forceinline__ float sigm(float x) { return __builtin_amdgcn_rcpf(1.f + __expf(-x)); }
; template <bool PASS2>
; __device__ __forceinline__ void ssm_block(const P& p, int blk) {
;     ...
; #pragma unroll
;         for (int rt = 0; rt < 2; ++rt) {
;           f32x4 acc = f32x4{0.f, 0.f, 0.f, 0.f};
; #pragma unroll
;           for (int kk = 0; kk < 4; ++kk) {
;             bf16x8 af = *(const bf16x8*)(xs + (rt * 16 + l15) * XS_STRIDE + kk * 32 + q4 * 8);
;             acc = __builtin_amdgcn_mfma_f32_16x16x32_bf16(af, cf[kk], acc, 0, 0, 0);
;           }
;           {
;             bf16x8 au = {0, 0, 0, 0, 0, 0, 0, 0};
;             if (q4 < 2) au = *(const bf16x8*)(proj + (size_t)(sc * 32 + rt * 16 + l15) * 4096 + 1536 + g * 16 + q4 * 8);
;             acc = __builtin_amdgcn_mfma_f32_16x16x32_bf16(au, df, acc, 0, 0, 0);
;           }
; #pragma unroll
;           for (int r = 0; r < 4; ++r) {
;             const int t = rt * 16 + q4 * 4 + r;
;             const float y = acc[r];
;             const float ge = y * sigm(1.5957691216057308f * (y + 0.044715f * y * y * y));
;             proj[(size_t)(sc * 32 + t) * 4096 + 1536 + g * 16 + l15] = f2bf(ge);
;           }
;         }
	v_mfma_f32_16x16x32_bf16 v[0:3], v[0:3], v[80:83], 0
	ds_read_b128 v[8:11], v130 offset:128
	s_waitcnt lgkmcnt(1)
	v_mfma_f32_16x16x32_bf16 v[0:3], v[4:7], v[84:87], v[0:3]
	ds_read_b128 v[4:7], v130 offset:192
	s_waitcnt vmcnt(1) lgkmcnt(1)
	v_mfma_f32_16x16x32_bf16 v[0:3], v[8:11], v[88:91], v[0:3]
	v_lshl_add_u64 v[10:11], v[114:115], 0, s[34:35]
	v_mov_b32_e32 v8, 0
	v_mov_b32_e32 v9, 0
	s_waitcnt vmcnt(0) lgkmcnt(0)
	v_mfma_f32_16x16x32_bf16 v[2:5], v[4:7], v[92:95], v[0:3]
	v_mov_b32_e32 v6, 0
	v_mov_b32_e32 v7, 0
	s_nop 0
	v_mov_b32_e32 v0, 0
	v_mfma_f32_16x16x32_bf16 v[2:5], v[132:135], v[96:99], v[2:5]
	v_lshl_add_u64 v[8:9], v[112:113], 0, s[34:35]
	ds_read_b128 v[20:23], v130 offset:4480
	ds_read_b128 v[16:19], v130 offset:4416
	s_nop 4
	v_mul_f32_e32 v1, 0x3d372713, v2
	v_mul_f32_e32 v1, v2, v1
	v_fma_f32 v1, v2, v1, v2
	v_mul_f32_e32 v1, 0x3fcc422a, v1
	v_mul_f32_e32 v1, 0xbfb8aa3b, v1
	v_mul_f32_e32 v6, 0x3d372713, v3
	v_exp_f32_e32 v1, v1
	v_mul_f32_e32 v6, v3, v6
	v_fma_f32 v6, v3, v6, v3
	v_mul_f32_e32 v6, 0x3fcc422a, v6
	v_mul_f32_e32 v6, 0xbfb8aa3b, v6
	v_add_f32_e32 v1, 1.0, v1
	v_exp_f32_e32 v6, v6
	v_rcp_f32_e32 v1, v1
	v_add_f32_e32 v6, 1.0, v6
	v_mul_f32_e32 v1, v2, v1
	v_mul_f32_e32 v2, 0x3d372713, v4
	v_rcp_f32_e32 v12, v6
	v_mul_f32_e32 v2, v4, v2
	v_add_co_u32_e32 v6, vcc, s38, v8
	v_fma_f32 v2, v4, v2, v4
	v_cvt_pk_bf16_f32 v1, v1, s0
	v_addc_co_u32_e32 v7, vcc, 0, v9, vcc
	v_mul_f32_e32 v2, 0x3fcc422a, v2
	global_store_short v[6:7], v1, off offset:3072
	v_mul_f32_e32 v2, 0xbfb8aa3b, v2
	v_mul_f32_e32 v7, 0x3d372713, v5
	v_mul_f32_e32 v1, v3, v12
	v_exp_f32_e32 v6, v2
	v_mul_f32_e32 v7, v5, v7
	ds_read_b128 v[12:15], v130 offset:4352
	v_fma_f32 v7, v5, v7, v5
	v_mul_f32_e32 v7, 0x3fcc422a, v7
	v_mul_f32_e32 v7, 0xbfb8aa3b, v7
	v_add_f32_e32 v6, 1.0, v6
	v_exp_f32_e32 v7, v7
	v_rcp_f32_e32 v6, v6
	v_add_co_u32_e32 v2, vcc, s39, v8
	v_cvt_pk_bf16_f32 v1, v1, s0
	s_nop 0
	v_addc_co_u32_e32 v3, vcc, 0, v9, vcc
	global_store_short v[2:3], v1, off offset:3072
	v_add_f32_e32 v2, 1.0, v7
	v_mul_f32_e32 v1, v4, v6
	v_rcp_f32_e32 v4, v2
	s_waitcnt lgkmcnt(0)
	v_mfma_f32_16x16x32_bf16 v[12:15], v[12:15], v[80:83], 0
	v_add_co_u32_e32 v2, vcc, s40, v8
	v_cvt_pk_bf16_f32 v1, v1, s0
	s_nop 0
	v_addc_co_u32_e32 v3, vcc, 0, v9, vcc
	global_store_short v[2:3], v1, off offset:3072
	v_mul_f32_e32 v1, v5, v4
	v_mfma_f32_16x16x32_bf16 v[2:5], v[16:19], v[84:87], v[12:15]
	v_add_co_u32_e32 v6, vcc, s41, v8
	v_cvt_pk_bf16_f32 v1, v1, s0
	s_nop 0
	ds_read_b128 v[12:15], v130 offset:4544
	v_mfma_f32_16x16x32_bf16 v[2:5], v[20:23], v[88:91], v[2:5]
	v_addc_co_u32_e32 v7, vcc, 0, v9, vcc
	global_store_short v[6:7], v1, off offset:3072
	s_waitcnt lgkmcnt(0)
	v_mfma_f32_16x16x32_bf16 v[4:7], v[12:15], v[92:95], v[2:5]
	v_mov_b32_e32 v1, 0
	s_nop 2
	v_mov_b32_e32 v2, 0
	v_mov_b32_e32 v3, 0
	s_branch .LBB0_352
